# gate/up GEMM loop: fragment ds_reads issued first in every load phase, SALU address/M0 arithmetic and LDS-DMA after them
# baseline (speedup 1.0000x reference)
; #define PG8_STAGE(bufoff, gbase, voff) do { _Pragma("unroll") for (int _i = 0; _i < 2; ++_i) \
;         __builtin_amdgcn_global_load_lds((const unsigned*)((const char*)(gbase) + (voff)[_i]), (LAS unsigned*)(lds + (bufoff) + ldsw + _i * 8192), 16, 0, 0); } while (0)
; #define PG8_LDA(dst, b, h) do { _Pragma("unroll") for (int m = 0; m < 4; ++m) _Pragma("unroll") for (int k = 0; k < 2; ++k) dst[m][k] = *(const LAS bf16x8*)(lds + PG8_SA(b, h) + aoff + m * 2048 + k * 1024); } while (0)
; #define PG8_LDB(dst, b, h) do { _Pragma("unroll") for (int n = 0; n < 2; ++n) _Pragma("unroll") for (int k = 0; k < 2; ++k) dst[n][k] = *(const LAS bf16x8*)(lds + PG8_SB(b, h) + boff + n * 2048 + k * 1024); } while (0)
; #define PG8_MMA(ai, bj, At, Bt) do { __builtin_amdgcn_s_setprio(1); _Pragma("unroll") for (int m = 0; m < 4; ++m) _Pragma("unroll") for (int n = 0; n < 2; ++n) _Pragma("unroll") for (int k = 0; k < 2; ++k) \
;         acc[ai][bj][m][n] = __builtin_amdgcn_mfma_f32_16x16x32_bf16(Bt[n][k], At[m][k], acc[ai][bj][m][n], 0, 0, 0); __builtin_amdgcn_s_setprio(0); } while (0)
; #define PG8_WAIT_V(n) asm volatile("s_waitcnt vmcnt(" #n ")" ::: "memory")
; #define PG8_WAIT_L(n) asm volatile("s_waitcnt lgkmcnt(" #n ")" ::: "memory")
; #define PG8_BAR __builtin_amdgcn_s_barrier()
; #define PG8_SCHED __builtin_amdgcn_sched_barrier(0)
; template <class Epi, class Sched, bool ALIGN_EPI>
; DI void gemm_phase(LAS unsigned char* lds, const Gemm g, const Sched& S, const Epi& E) {
;     ...
;             const bool last = (t == nt - 2);
;             const char* a1 = cA + (size_t)(t + 1) * kstep;
;             const char* a2 = last ? nA : cA + (size_t)(t + 2) * kstep; const char* b2 = last ? nB : cB + (size_t)(t + 2) * kstep;
;             const char* a3 = a2 + kstep; const char* b3 = b2 + kstep;
;             PG8_LDB(B0, 0, 0); PG8_LDB(B1, 0, 1); PG8_SCHED; PG8_LDA(At, 0, 0); PG8_STAGE(PG8_SA(1, 1), a1 + hstep, voffA);
;             PG8_WAIT_V(8); PG8_WAIT_L(0); PG8_BAR; PG8_MMA(0, 0, At, B0); PG8_MMA(0, 1, At, B1); PG8_BAR; PG8_SCHED;
;             PG8_LDA(At, 0, 1); PG8_STAGE(PG8_SB(0, 0), b2, voffA); PG8_STAGE(PG8_SB(0, 1), b2 + hstep, voffA); PG8_STAGE(PG8_SA(0, 0), a2, voffA);
;             PG8_WAIT_V(8); PG8_WAIT_L(0); PG8_BAR; PG8_MMA(1, 0, At, B0); PG8_MMA(1, 1, At, B1); PG8_BAR; PG8_SCHED;
.LBB0_826:
	ds_read_b128 v[44:47], v206
	ds_read_b128 v[48:51], v206 offset:1024
	ds_read_b128 v[52:55], v206 offset:2048
	ds_read_b128 v[56:59], v206 offset:3072
	ds_read_b128 v[124:127], v206 offset:16384
	ds_read_b128 v[128:131], v206 offset:17408
	ds_read_b128 v[132:135], v206 offset:18432
	ds_read_b128 v[136:139], v206 offset:19456
	ds_read_b128 v[160:163], v245
	ds_read_b128 v[164:167], v245 offset:1024
	ds_read_b128 v[182:185], v245 offset:2048
	ds_read_b128 v[186:189], v245 offset:3072
	ds_read_b128 v[190:193], v245 offset:4096
	ds_read_b128 v[194:197], v245 offset:5120
	ds_read_b128 v[198:201], v245 offset:6144
	ds_read_b128 v[202:205], v245 offset:7168
	s_add_u32 s30, s0, 0xfffc0080
	s_addc_u32 s31, s1, -1
	s_add_i32 s46, 0, 0x10000
	s_cmp_eq_u32 s45, 12
	s_cselect_b32 s35, s25, s31
	s_cselect_b32 s34, s24, s30
	s_cselect_b32 s31, s23, s44
	s_cselect_b32 s30, s29, s43
	s_add_i32 s52, 0, 0x14000
	s_add_i32 m0, s93, 0xc000
	s_nop 0
	global_load_lds_dwordx4 v178, s[0:1]
	s_add_i32 m0, s93, 0xe000
	s_nop 0
	global_load_lds_dwordx4 v180, s[0:1]
	s_waitcnt vmcnt(8)
	s_waitcnt lgkmcnt(0)
	s_barrier
	s_setprio 1
	s_waitcnt lgkmcnt(0)
	v_mfma_f32_16x16x32_bf16 v[156:159], v[44:47], v[160:163], v[156:159]
	v_mfma_f32_16x16x32_bf16 v[76:79], v[52:55], v[160:163], v[76:79]
	v_mfma_f32_16x16x32_bf16 v[148:151], v[44:47], v[182:185], v[148:151]
	v_mfma_f32_16x16x32_bf16 v[68:71], v[52:55], v[182:185], v[68:71]
	v_mfma_f32_16x16x32_bf16 v[140:143], v[44:47], v[190:193], v[140:143]
	v_mfma_f32_16x16x32_bf16 v[60:63], v[52:55], v[190:193], v[60:63]
	v_mfma_f32_16x16x32_bf16 v[116:119], v[44:47], v[198:201], v[116:119]
	v_mfma_f32_16x16x32_bf16 v[36:39], v[52:55], v[198:201], v[36:39]
	v_mfma_f32_16x16x32_bf16 v[156:159], v[48:51], v[164:167], v[156:159]
	v_mfma_f32_16x16x32_bf16 v[76:79], v[56:59], v[164:167], v[76:79]
	v_mfma_f32_16x16x32_bf16 v[148:151], v[48:51], v[186:189], v[148:151]
	v_mfma_f32_16x16x32_bf16 v[68:71], v[56:59], v[186:189], v[68:71]
	v_mfma_f32_16x16x32_bf16 v[140:143], v[48:51], v[194:197], v[140:143]
	v_mfma_f32_16x16x32_bf16 v[60:63], v[56:59], v[194:197], v[60:63]
	v_mfma_f32_16x16x32_bf16 v[116:119], v[48:51], v[202:205], v[116:119]
	v_mfma_f32_16x16x32_bf16 v[36:39], v[56:59], v[202:205], v[36:39]
	s_setprio 0
	s_setprio 1
	v_mfma_f32_16x16x32_bf16 v[152:155], v[124:127], v[160:163], v[152:155]
	v_mfma_f32_16x16x32_bf16 v[72:75], v[132:135], v[160:163], v[72:75]
	v_mfma_f32_16x16x32_bf16 v[144:147], v[124:127], v[182:185], v[144:147]
	v_mfma_f32_16x16x32_bf16 v[64:67], v[132:135], v[182:185], v[64:67]
	v_mfma_f32_16x16x32_bf16 v[120:123], v[124:127], v[190:193], v[120:123]
	v_mfma_f32_16x16x32_bf16 v[40:43], v[132:135], v[190:193], v[40:43]
	v_mfma_f32_16x16x32_bf16 v[112:115], v[124:127], v[198:201], v[112:115]
	v_mfma_f32_16x16x32_bf16 v[32:35], v[132:135], v[198:201], v[32:35]
	v_mfma_f32_16x16x32_bf16 v[152:155], v[128:131], v[164:167], v[152:155]
	v_mfma_f32_16x16x32_bf16 v[72:75], v[136:139], v[164:167], v[72:75]
	v_mfma_f32_16x16x32_bf16 v[144:147], v[128:131], v[186:189], v[144:147]
	v_mfma_f32_16x16x32_bf16 v[64:67], v[136:139], v[186:189], v[64:67]
	v_mfma_f32_16x16x32_bf16 v[120:123], v[128:131], v[194:197], v[120:123]
	v_mfma_f32_16x16x32_bf16 v[40:43], v[136:139], v[194:197], v[40:43]
	v_mfma_f32_16x16x32_bf16 v[112:115], v[128:131], v[202:205], v[112:115]
	v_mfma_f32_16x16x32_bf16 v[32:35], v[136:139], v[202:205], v[32:35]
	s_setprio 0
	s_barrier
	ds_read_b128 v[160:163], v245 offset:16384
	ds_read_b128 v[164:167], v245 offset:17408
	ds_read_b128 v[182:185], v245 offset:18432
	ds_read_b128 v[186:189], v245 offset:19456
	ds_read_b128 v[190:193], v245 offset:20480
	ds_read_b128 v[194:197], v245 offset:21504
	ds_read_b128 v[198:201], v245 offset:22528
	ds_read_b128 v[202:205], v245 offset:23552
	s_add_i32 s46, s46, s92
	s_add_u32 s94, s30, s2
	s_addc_u32 s95, s31, s3
	s_add_u32 s96, s34, s2
	s_addc_u32 s97, s35, s3
	s_mov_b32 m0, s46
	s_nop 0
	global_load_lds_dwordx4 v174, s[30:31]
	s_add_i32 m0, s46, 0x2000
	s_add_u32 s46, s30, 0x40000
	s_addc_u32 s47, s31, 0
	s_add_i32 s52, s52, s92
	global_load_lds_dwordx4 v176, s[30:31]
	s_mov_b32 m0, s52
	s_nop 0
	global_load_lds_dwordx4 v174, s[46:47]
	s_add_i32 m0, s52, 0x2000
	s_nop 0
	global_load_lds_dwordx4 v176, s[46:47]
	s_mov_b32 m0, s93
	s_nop 0
	global_load_lds_dwordx4 v174, s[34:35]
	s_mov_b32 m0, s86
	s_nop 0
	global_load_lds_dwordx4 v176, s[34:35]
	s_waitcnt vmcnt(8)
	s_waitcnt lgkmcnt(0)
	s_barrier
	s_setprio 1
	s_waitcnt lgkmcnt(0)
	v_mfma_f32_16x16x32_bf16 v[108:111], v[44:47], v[160:163], v[108:111]
	v_mfma_f32_16x16x32_bf16 v[28:31], v[52:55], v[160:163], v[28:31]
	v_mfma_f32_16x16x32_bf16 v[100:103], v[44:47], v[182:185], v[100:103]
	v_mfma_f32_16x16x32_bf16 v[20:23], v[52:55], v[182:185], v[20:23]
	v_mfma_f32_16x16x32_bf16 v[92:95], v[44:47], v[190:193], v[92:95]
	v_mfma_f32_16x16x32_bf16 v[12:15], v[52:55], v[190:193], v[12:15]
	v_mfma_f32_16x16x32_bf16 v[4:7], v[52:55], v[198:201], v[4:7]
	v_mfma_f32_16x16x32_bf16 v[108:111], v[48:51], v[164:167], v[108:111]
	v_mfma_f32_16x16x32_bf16 v[28:31], v[56:59], v[164:167], v[28:31]
	v_mfma_f32_16x16x32_bf16 v[100:103], v[48:51], v[186:189], v[100:103]
	v_mfma_f32_16x16x32_bf16 v[20:23], v[56:59], v[186:189], v[20:23]
	v_mfma_f32_16x16x32_bf16 v[92:95], v[48:51], v[194:197], v[92:95]
	v_mfma_f32_16x16x32_bf16 v[12:15], v[56:59], v[194:197], v[12:15]
	v_mfma_f32_16x16x32_bf16 v[44:47], v[44:47], v[198:201], v[84:87]
	v_mfma_f32_16x16x32_bf16 v[4:7], v[56:59], v[202:205], v[4:7]
	v_mfma_f32_16x16x32_bf16 v[44:47], v[48:51], v[202:205], v[44:47]
	s_setprio 0
	s_setprio 1
	v_mfma_f32_16x16x32_bf16 v[24:27], v[132:135], v[160:163], v[24:27]
	v_mfma_f32_16x16x32_bf16 v[16:19], v[132:135], v[182:185], v[16:19]
	v_mfma_f32_16x16x32_bf16 v[8:11], v[132:135], v[190:193], v[8:11]
	v_mfma_f32_16x16x32_bf16 v[80:83], v[124:127], v[198:201], v[80:83]
	v_mfma_f32_16x16x32_bf16 v[0:3], v[132:135], v[198:201], v[0:3]
	v_mfma_f32_16x16x32_bf16 v[48:51], v[124:127], v[160:163], v[104:107]
	v_mfma_f32_16x16x32_bf16 v[24:27], v[136:139], v[164:167], v[24:27]
	v_mfma_f32_16x16x32_bf16 v[52:55], v[124:127], v[182:185], v[96:99]
	v_mfma_f32_16x16x32_bf16 v[16:19], v[136:139], v[186:189], v[16:19]
	v_mfma_f32_16x16x32_bf16 v[56:59], v[124:127], v[190:193], v[88:91]
	v_mfma_f32_16x16x32_bf16 v[8:11], v[136:139], v[194:197], v[8:11]
	v_mfma_f32_16x16x32_bf16 v[80:83], v[128:131], v[202:205], v[80:83]
	v_mfma_f32_16x16x32_bf16 v[0:3], v[136:139], v[202:205], v[0:3]
	v_mfma_f32_16x16x32_bf16 v[48:51], v[128:131], v[164:167], v[48:51]
	v_mfma_f32_16x16x32_bf16 v[52:55], v[128:131], v[186:189], v[52:55]
	v_mfma_f32_16x16x32_bf16 v[56:59], v[128:131], v[194:197], v[56:59]
	s_setprio 0
	s_barrier
; #define PG8_STAGE(bufoff, gbase, voff) do { _Pragma("unroll") for (int _i = 0; _i < 2; ++_i) \
;         __builtin_amdgcn_global_load_lds((const unsigned*)((const char*)(gbase) + (voff)[_i]), (LAS unsigned*)(lds + (bufoff) + ldsw + _i * 8192), 16, 0, 0); } while (0)
; #define PG8_LDA(dst, b, h) do { _Pragma("unroll") for (int m = 0; m < 4; ++m) _Pragma("unroll") for (int k = 0; k < 2; ++k) dst[m][k] = *(const LAS bf16x8*)(lds + PG8_SA(b, h) + aoff + m * 2048 + k * 1024); } while (0)
; #define PG8_LDB(dst, b, h) do { _Pragma("unroll") for (int n = 0; n < 2; ++n) _Pragma("unroll") for (int k = 0; k < 2; ++k) dst[n][k] = *(const LAS bf16x8*)(lds + PG8_SB(b, h) + boff + n * 2048 + k * 1024); } while (0)
; #define PG8_MMA(ai, bj, At, Bt) do { __builtin_amdgcn_s_setprio(1); _Pragma("unroll") for (int m = 0; m < 4; ++m) _Pragma("unroll") for (int n = 0; n < 2; ++n) _Pragma("unroll") for (int k = 0; k < 2; ++k) \
;         acc[ai][bj][m][n] = __builtin_amdgcn_mfma_f32_16x16x32_bf16(Bt[n][k], At[m][k], acc[ai][bj][m][n], 0, 0, 0); __builtin_amdgcn_s_setprio(0); } while (0)
; #define PG8_WAIT_V(n) asm volatile("s_waitcnt vmcnt(" #n ")" ::: "memory")
; #define PG8_WAIT_L(n) asm volatile("s_waitcnt lgkmcnt(" #n ")" ::: "memory")
; #define PG8_BAR __builtin_amdgcn_s_barrier()
; #define PG8_SCHED __builtin_amdgcn_sched_barrier(0)
; template <class Epi, class Sched, bool ALIGN_EPI>
; DI void gemm_phase(LAS unsigned char* lds, const Gemm g, const Sched& S, const Epi& E) {
;     ...
;             PG8_LDB(B0, 1, 0); PG8_LDB(B1, 1, 1); PG8_SCHED; PG8_LDA(At, 1, 0); PG8_STAGE(PG8_SA(0, 1), a2 + hstep, voffA);
;             PG8_WAIT_V(8); PG8_WAIT_L(0); PG8_BAR; PG8_MMA(0, 0, At, B0); PG8_MMA(0, 1, At, B1); PG8_BAR; PG8_SCHED;
;             PG8_LDA(At, 1, 1); PG8_STAGE(PG8_SB(1, 0), b3, voffA); PG8_STAGE(PG8_SB(1, 1), b3 + hstep, voffA); PG8_STAGE(PG8_SA(1, 0), a3, voffA);
;             PG8_WAIT_V(8); PG8_WAIT_L(0); PG8_BAR; PG8_MMA(1, 0, At, B0); PG8_MMA(1, 1, At, B1); PG8_BAR; PG8_SCHED;
;         }
	ds_read_b128 v[84:87], v206 offset:32768
	ds_read_b128 v[88:91], v206 offset:33792
	ds_read_b128 v[96:99], v206 offset:34816
	ds_read_b128 v[104:107], v206 offset:35840
	ds_read_b128 v[124:127], v206 offset:49152
	ds_read_b128 v[128:131], v206 offset:50176
	ds_read_b128 v[132:135], v206 offset:51200
	ds_read_b128 v[136:139], v206 offset:52224
	ds_read_b128 v[160:163], v245 offset:32768
	ds_read_b128 v[164:167], v245 offset:33792
	ds_read_b128 v[182:185], v245 offset:34816
	ds_read_b128 v[186:189], v245 offset:35840
	ds_read_b128 v[190:193], v245 offset:36864
	ds_read_b128 v[194:197], v245 offset:37888
	ds_read_b128 v[198:201], v245 offset:38912
	ds_read_b128 v[202:205], v245 offset:39936
	s_add_i32 s46, 0, 0x18000
	s_add_i32 s47, 0, 0x1c000
	s_add_u32 s34, s34, 0x40000
	s_addc_u32 s35, s35, 0
	s_mov_b32 m0, s33
	s_nop 0
	global_load_lds_dwordx4 v174, s[34:35]
	s_mov_b32 m0, s78
	s_nop 0
	global_load_lds_dwordx4 v176, s[34:35]
	s_waitcnt vmcnt(8)
	s_waitcnt lgkmcnt(0)
	s_barrier
	s_setprio 1
	s_waitcnt lgkmcnt(0)
	v_mfma_f32_16x16x32_bf16 v[156:159], v[84:87], v[160:163], v[156:159]
	v_mfma_f32_16x16x32_bf16 v[76:79], v[96:99], v[160:163], v[76:79]
	v_mfma_f32_16x16x32_bf16 v[148:151], v[84:87], v[182:185], v[148:151]
	v_mfma_f32_16x16x32_bf16 v[68:71], v[96:99], v[182:185], v[68:71]
	v_mfma_f32_16x16x32_bf16 v[140:143], v[84:87], v[190:193], v[140:143]
	v_mfma_f32_16x16x32_bf16 v[60:63], v[96:99], v[190:193], v[60:63]
	v_mfma_f32_16x16x32_bf16 v[116:119], v[84:87], v[198:201], v[116:119]
	v_mfma_f32_16x16x32_bf16 v[36:39], v[96:99], v[198:201], v[36:39]
	v_mfma_f32_16x16x32_bf16 v[156:159], v[88:91], v[164:167], v[156:159]
	v_mfma_f32_16x16x32_bf16 v[76:79], v[104:107], v[164:167], v[76:79]
	v_mfma_f32_16x16x32_bf16 v[148:151], v[88:91], v[186:189], v[148:151]
	v_mfma_f32_16x16x32_bf16 v[68:71], v[104:107], v[186:189], v[68:71]
	v_mfma_f32_16x16x32_bf16 v[140:143], v[88:91], v[194:197], v[140:143]
	v_mfma_f32_16x16x32_bf16 v[60:63], v[104:107], v[194:197], v[60:63]
	v_mfma_f32_16x16x32_bf16 v[116:119], v[88:91], v[202:205], v[116:119]
	v_mfma_f32_16x16x32_bf16 v[36:39], v[104:107], v[202:205], v[36:39]
	s_setprio 0
	s_setprio 1
	v_mfma_f32_16x16x32_bf16 v[152:155], v[124:127], v[160:163], v[152:155]
	v_mfma_f32_16x16x32_bf16 v[72:75], v[132:135], v[160:163], v[72:75]
	v_mfma_f32_16x16x32_bf16 v[144:147], v[124:127], v[182:185], v[144:147]
	v_mfma_f32_16x16x32_bf16 v[64:67], v[132:135], v[182:185], v[64:67]
	v_mfma_f32_16x16x32_bf16 v[120:123], v[124:127], v[190:193], v[120:123]
	v_mfma_f32_16x16x32_bf16 v[40:43], v[132:135], v[190:193], v[40:43]
	v_mfma_f32_16x16x32_bf16 v[112:115], v[124:127], v[198:201], v[112:115]
	v_mfma_f32_16x16x32_bf16 v[32:35], v[132:135], v[198:201], v[32:35]
	v_mfma_f32_16x16x32_bf16 v[152:155], v[128:131], v[164:167], v[152:155]
	v_mfma_f32_16x16x32_bf16 v[72:75], v[136:139], v[164:167], v[72:75]
	v_mfma_f32_16x16x32_bf16 v[144:147], v[128:131], v[186:189], v[144:147]
	v_mfma_f32_16x16x32_bf16 v[64:67], v[136:139], v[186:189], v[64:67]
	v_mfma_f32_16x16x32_bf16 v[120:123], v[128:131], v[194:197], v[120:123]
	v_mfma_f32_16x16x32_bf16 v[40:43], v[136:139], v[194:197], v[40:43]
	v_mfma_f32_16x16x32_bf16 v[112:115], v[128:131], v[202:205], v[112:115]
	v_mfma_f32_16x16x32_bf16 v[32:35], v[136:139], v[202:205], v[32:35]
	s_setprio 0
	s_barrier
	ds_read_b128 v[160:163], v245 offset:49152
	ds_read_b128 v[164:167], v245 offset:50176
	ds_read_b128 v[182:185], v245 offset:51200
	ds_read_b128 v[186:189], v245 offset:52224
	ds_read_b128 v[190:193], v245 offset:53248
	ds_read_b128 v[194:197], v245 offset:54272
	ds_read_b128 v[198:201], v245 offset:55296
	ds_read_b128 v[202:205], v245 offset:56320
	s_add_i32 s34, s46, s92
	s_mov_b32 m0, s34
	s_nop 0
	global_load_lds_dwordx4 v174, s[94:95]
	s_add_i32 m0, s34, 0x2000
	s_add_u32 s30, s30, 0x40080
	s_addc_u32 s31, s31, 0
	s_add_i32 s34, s47, s92
	global_load_lds_dwordx4 v176, s[94:95]
	s_mov_b32 m0, s34
	s_nop 0
	global_load_lds_dwordx4 v174, s[30:31]
	s_add_i32 m0, s34, 0x2000
	s_nop 0
	global_load_lds_dwordx4 v176, s[30:31]
	s_mov_b32 m0, s8
	s_nop 0
	global_load_lds_dwordx4 v174, s[96:97]
	s_mov_b32 m0, s9
	s_nop 0
	global_load_lds_dwordx4 v176, s[96:97]
	s_waitcnt vmcnt(8)
	s_waitcnt lgkmcnt(0)
	s_barrier
	s_setprio 1
	s_waitcnt lgkmcnt(0)
	v_mfma_f32_16x16x32_bf16 v[108:111], v[84:87], v[160:163], v[108:111]
	v_mfma_f32_16x16x32_bf16 v[28:31], v[96:99], v[160:163], v[28:31]
	v_mfma_f32_16x16x32_bf16 v[100:103], v[84:87], v[182:185], v[100:103]
	v_mfma_f32_16x16x32_bf16 v[20:23], v[96:99], v[182:185], v[20:23]
	v_mfma_f32_16x16x32_bf16 v[92:95], v[84:87], v[190:193], v[92:95]
	v_mfma_f32_16x16x32_bf16 v[12:15], v[96:99], v[190:193], v[12:15]
	v_mfma_f32_16x16x32_bf16 v[44:47], v[84:87], v[198:201], v[44:47]
	v_mfma_f32_16x16x32_bf16 v[4:7], v[96:99], v[198:201], v[4:7]
	v_mfma_f32_16x16x32_bf16 v[108:111], v[88:91], v[164:167], v[108:111]
	v_mfma_f32_16x16x32_bf16 v[28:31], v[104:107], v[164:167], v[28:31]
	v_mfma_f32_16x16x32_bf16 v[100:103], v[88:91], v[186:189], v[100:103]
	v_mfma_f32_16x16x32_bf16 v[20:23], v[104:107], v[186:189], v[20:23]
	v_mfma_f32_16x16x32_bf16 v[92:95], v[88:91], v[194:197], v[92:95]
	v_mfma_f32_16x16x32_bf16 v[12:15], v[104:107], v[194:197], v[12:15]
	v_mfma_f32_16x16x32_bf16 v[84:87], v[88:91], v[202:205], v[44:47]
	v_mfma_f32_16x16x32_bf16 v[4:7], v[104:107], v[202:205], v[4:7]
	s_setprio 0
	s_setprio 1
	v_mfma_f32_16x16x32_bf16 v[44:47], v[124:127], v[160:163], v[48:51]
	v_mfma_f32_16x16x32_bf16 v[104:107], v[128:131], v[164:167], v[44:47]
	v_mfma_f32_16x16x32_bf16 v[44:47], v[124:127], v[182:185], v[52:55]
	v_mfma_f32_16x16x32_bf16 v[96:99], v[128:131], v[186:189], v[44:47]
	v_mfma_f32_16x16x32_bf16 v[44:47], v[124:127], v[190:193], v[56:59]
	v_mfma_f32_16x16x32_bf16 v[24:27], v[132:135], v[160:163], v[24:27]
	v_mfma_f32_16x16x32_bf16 v[16:19], v[132:135], v[182:185], v[16:19]
	v_mfma_f32_16x16x32_bf16 v[88:91], v[128:131], v[194:197], v[44:47]
	v_mfma_f32_16x16x32_bf16 v[8:11], v[132:135], v[190:193], v[8:11]
	v_mfma_f32_16x16x32_bf16 v[44:47], v[124:127], v[198:201], v[80:83]
	v_mfma_f32_16x16x32_bf16 v[0:3], v[132:135], v[198:201], v[0:3]
	v_mfma_f32_16x16x32_bf16 v[24:27], v[136:139], v[164:167], v[24:27]
	v_mfma_f32_16x16x32_bf16 v[16:19], v[136:139], v[186:189], v[16:19]
	v_mfma_f32_16x16x32_bf16 v[8:11], v[136:139], v[194:197], v[8:11]
	v_mfma_f32_16x16x32_bf16 v[80:83], v[128:131], v[202:205], v[44:47]
	v_mfma_f32_16x16x32_bf16 v[0:3], v[136:139], v[202:205], v[0:3]
	s_setprio 0
	s_barrier
	s_add_i32 s45, s45, 2
	s_add_u32 s0, s0, 0x100
	s_addc_u32 s1, s1, 0
	s_add_u32 s43, s43, 0x100
	s_addc_u32 s44, s44, 0
	s_cmp_gt_u32 s45, 13
	s_cbranch_scc0 .LBB0_826
	s_and_b64 vcc, exec, s[18:19]
	s_cbranch_vccz .LBB0_829
	s_barrier
